# barrier: non-leaders poll the global release generation directly (one hop less)
# baseline (speedup 1.0000x reference)
; __device__ __forceinline__ unsigned xb_ld(unsigned* p)              { return __hip_atomic_load(p, __ATOMIC_RELAXED, __HIP_MEMORY_SCOPE_AGENT); }
; __device__ __forceinline__ unsigned xb_add(unsigned* p, unsigned v) { return __hip_atomic_fetch_add(p, v, __ATOMIC_RELAXED, __HIP_MEMORY_SCOPE_AGENT); }
; #define XB_SPIN(cond, bar) do { unsigned _sp = 0; while (cond) { __builtin_amdgcn_s_sleep(1); \
;     if ((++_sp & 255u) == 0u) { if (xb_ld(&(bar)[XB_TMO])) break; if (_sp > XB_SPIN_CAP) { atomicAdd(&(bar)[XB_TMO], 1u); break; } } } } while (0)
; __device__ __forceinline__ void xcd_barrier(const XcdBarrier& b) {
;     ...
;         const unsigned old = xb_add(&bar[XB_XSUB(b.x)], 1u);
;         const unsigned gen = old / nloc;
;         if (old + 1u == (gen + 1u) * nloc) {
;             __builtin_amdgcn_fence(__ATOMIC_RELEASE, "agent");
;             asm volatile("s_waitcnt vmcnt(0)" ::: "memory");
;             const unsigned og = xb_add(&bar[XB_TOP], 1u);
;             const unsigned tg = og / nx;
;             if (og + 1u == (tg + 1u) * nx) xb_add(&bar[XB_TOPGEN], 1u);
;             else XB_SPIN(xb_ld(&bar[XB_TOPGEN]) == tg, bar);
;             __builtin_amdgcn_fence(__ATOMIC_ACQUIRE, "agent");
;             xb_add(&bar[XB_XGEN(b.x)], 1u);
;             asm volatile("s_waitcnt vmcnt(0)" ::: "memory");
;         } else {
;             XB_SPIN(xb_ld(&bar[XB_XGEN(b.x)]) == gen, bar);
.LBB0_380:
	s_or_b64 exec, exec, s[6:7]
	buffer_inv sc1
	v_cvt_f32_u32_e32 v4, v2
	s_waitcnt vmcnt(1)
	v_readfirstlane_b32 s2, v3
	v_sub_u32_e32 v3, 0, v2
	v_rcp_iflag_f32_e32 v4, v4
	v_add_u32_e32 v5, s2, v1
	v_mul_f32_e32 v4, 0x4f7ffffe, v4
	v_cvt_u32_f32_e32 v4, v4
	v_mul_lo_u32 v1, v3, v4
	v_mul_hi_u32 v1, v4, v1
	v_add_u32_e32 v1, v4, v1
	v_mul_hi_u32 v1, v5, v1
	v_mul_lo_u32 v3, v1, v2
	v_sub_u32_e32 v3, v5, v3
	v_add_u32_e32 v4, 1, v1
	v_cmp_ge_u32_e32 vcc, v3, v2
	s_nop 1
	v_cndmask_b32_e32 v1, v1, v4, vcc
	v_sub_u32_e32 v4, v3, v2
	v_cndmask_b32_e32 v3, v3, v4, vcc
	v_add_u32_e32 v4, 1, v1
	v_cmp_ge_u32_e32 vcc, v3, v2
	v_add_u32_e32 v3, 1, v5
	s_nop 0
	v_cndmask_b32_e32 v1, v1, v4, vcc
	v_mul_lo_u32 v4, v2, v1
	v_add_u32_e32 v2, v4, v2
	v_cmp_ne_u32_e32 vcc, v3, v2
	s_and_saveexec_b64 s[6:7], vcc
	s_xor_b64 s[6:7], exec, s[6:7]
	s_cbranch_execz .LBB0_394
	v_readlane_b32 s8, v253, 42
	v_readlane_b32 s9, v253, 43
	s_waitcnt lgkmcnt(0)
	s_nop 3
	global_load_dword v0, v193, s[8:9] sc1
	s_waitcnt vmcnt(0)
	v_cmp_eq_u32_e32 vcc, v0, v1
	s_and_saveexec_b64 s[8:9], vcc
	s_cbranch_execz .LBB0_393
	s_mov_b32 s2, 1
	s_mov_b64 s[10:11], 0
	s_branch .LBB0_384

; __device__ __forceinline__ unsigned xb_ld(unsigned* p)              { return __hip_atomic_load(p, __ATOMIC_RELAXED, __HIP_MEMORY_SCOPE_AGENT); }
; #define XB_SPIN(cond, bar) do { unsigned _sp = 0; while (cond) { __builtin_amdgcn_s_sleep(1); \
;     if ((++_sp & 255u) == 0u) { if (xb_ld(&(bar)[XB_TMO])) break; if (_sp > XB_SPIN_CAP) { atomicAdd(&(bar)[XB_TMO], 1u); break; } } } } while (0)
; __device__ __forceinline__ void xcd_barrier(const XcdBarrier& b) {
;     ...
;             XB_SPIN(xb_ld(&bar[XB_XGEN(b.x)]) == gen, bar);
.LBB0_388:
	v_readlane_b32 s14, v253, 42
	v_readlane_b32 s15, v253, 43
	s_add_i32 s2, s2, 1
	s_mov_b64 s[16:17], -1
	s_nop 2
	global_load_dword v0, v193, s[14:15] sc1
	s_waitcnt vmcnt(0)
	v_cmp_ne_u32_e32 vcc, v0, v1
	s_orn2_b64 s[14:15], vcc, exec
	s_branch .LBB0_383
